# same V-fragment direct-read rewrite applied to the sliding-window branch P.V section as well (selected + sliding-window)
# speedup vs baseline: 1.0062x; 1.0012x over previous
.LBB0_784:
	v_exp_f32_e32 v2, v132
	v_exp_f32_e32 v3, v133
	v_exp_f32_e32 v116, v116
	v_exp_f32_e32 v117, v117
	v_exp_f32_e32 v132, v134
	v_exp_f32_e32 v133, v135
	v_exp_f32_e32 v124, v124
	v_exp_f32_e32 v125, v125
	v_exp_f32_e32 v126, v126
	v_exp_f32_e32 v127, v127
	v_exp_f32_e32 v120, v120
	v_exp_f32_e32 v121, v121
	v_exp_f32_e32 v122, v122
	v_exp_f32_e32 v123, v123
	v_exp_f32_e32 v134, v118
	v_exp_f32_e32 v135, v119
	v_exp_f32_e32 v174, v136
	v_exp_f32_e32 v177, v137
	v_exp_f32_e32 v138, v138
	v_exp_f32_e32 v139, v139
	v_exp_f32_e32 v178, v128
	v_exp_f32_e32 v179, v129
	v_exp_f32_e32 v180, v130
	v_exp_f32_e32 v181, v131
	v_exp_f32_e32 v140, v140
	v_exp_f32_e32 v141, v141
	v_exp_f32_e32 v142, v142
	v_exp_f32_e32 v143, v143
	v_exp_f32_e32 v144, v144
	v_exp_f32_e32 v145, v145
	v_exp_f32_e32 v146, v146
	v_exp_f32_e32 v147, v147
	v_cvt_pk_bf16_f32 v118, v2, v3
	v_add3_u32 v3, s75, v167, v168
	v_cvt_pk_bf16_f32 v120, v120, v121
	v_cvt_pk_bf16_f32 v121, v122, v123
	v_cvt_pk_bf16_f32 v122, v124, v125
	v_cvt_pk_bf16_f32 v124, v116, v117
	v_lshl_add_u32 v116, v169, 1, v3
	v_lshl_add_u32 v117, v170, 1, v3
	v_cvt_pk_bf16_f32 v119, v132, v133
	v_cvt_pk_bf16_f32 v123, v126, v127
	v_cvt_pk_bf16_f32 v125, v134, v135
	v_lshl_add_u32 v2, v171, 1, v3
	v_lshl_add_u32 v3, v172, 1, v3
	s_andn2_b64 vcc, exec, s[30:31]
	ds_read_b64 v[134:135], v116 offset:8192
	ds_read_b64 v[136:137], v117 offset:8192
	ds_read_b64 v[130:131], v116 offset:10240
	ds_read_b64 v[132:133], v117 offset:10240
	s_waitcnt lgkmcnt(2)
	s_nop 0
	v_mfma_f32_16x16x32_bf16 v[72:75], v[134:137], v[118:121], v[72:75]
	v_mfma_f32_16x16x32_bf16 v[36:39], v[134:137], v[122:125], v[36:39]
	ds_read_b64 v[126:127], v116 offset:12288
	ds_read_b64 v[128:129], v117 offset:12288
	ds_read_b64 v[134:135], v116 offset:14336
	ds_read_b64 v[136:137], v117 offset:14336
	s_waitcnt lgkmcnt(4)
	v_mfma_f32_16x16x32_bf16 v[68:71], v[130:133], v[118:121], v[68:71]
	v_mfma_f32_16x16x32_bf16 v[32:35], v[130:133], v[122:125], v[32:35]
	s_waitcnt lgkmcnt(2)
	v_mfma_f32_16x16x32_bf16 v[64:67], v[126:129], v[118:121], v[64:67]
	ds_read_b64 v[130:131], v2 offset:8192
	ds_read_b64 v[132:133], v3 offset:8192
	v_mfma_f32_16x16x32_bf16 v[28:31], v[126:129], v[122:125], v[28:31]
	s_waitcnt lgkmcnt(2)
	v_mfma_f32_16x16x32_bf16 v[56:59], v[134:137], v[118:121], v[56:59]
	v_mfma_f32_16x16x32_bf16 v[24:27], v[134:137], v[122:125], v[24:27]
	ds_read_b64 v[126:127], v2 offset:10240
	ds_read_b64 v[128:129], v3 offset:10240
	v_mfma_f32_16x16x32_bf16 v[112:115], v[20:23], v[118:121], v[112:115]
	v_cvt_pk_bf16_f32 v118, v174, v177
	v_cvt_pk_bf16_f32 v119, v138, v139
	v_cvt_pk_bf16_f32 v120, v140, v141
	v_mfma_f32_16x16x32_bf16 v[76:79], v[20:23], v[122:125], v[76:79]
	v_cvt_pk_bf16_f32 v121, v142, v143
	v_cvt_pk_bf16_f32 v122, v178, v179
	v_cvt_pk_bf16_f32 v123, v180, v181
	v_cvt_pk_bf16_f32 v124, v144, v145
	v_cvt_pk_bf16_f32 v125, v146, v147
	s_waitcnt lgkmcnt(2)
	s_nop 0
	v_mfma_f32_16x16x32_bf16 v[72:75], v[130:133], v[118:121], v[72:75]
	v_mfma_f32_16x16x32_bf16 v[36:39], v[130:133], v[122:125], v[36:39]
	ds_read_b64 v[134:135], v2 offset:12288
	ds_read_b64 v[136:137], v3 offset:12288
	ds_read_b64 v[130:131], v2 offset:14336
	ds_read_b64 v[132:133], v3 offset:14336
	s_waitcnt lgkmcnt(4)
	v_mfma_f32_16x16x32_bf16 v[68:71], v[126:129], v[118:121], v[68:71]
	v_mfma_f32_16x16x32_bf16 v[32:35], v[126:129], v[122:125], v[32:35]
	v_mfma_f32_16x16x32_bf16 v[112:115], v[20:23], v[118:121], v[112:115]
	v_mfma_f32_16x16x32_bf16 v[76:79], v[20:23], v[122:125], v[76:79]
	s_waitcnt lgkmcnt(2)
	v_mfma_f32_16x16x32_bf16 v[64:67], v[134:137], v[118:121], v[64:67]
	v_mfma_f32_16x16x32_bf16 v[28:31], v[134:137], v[122:125], v[28:31]
	s_waitcnt lgkmcnt(0)
	v_mfma_f32_16x16x32_bf16 v[56:59], v[130:133], v[118:121], v[56:59]
	v_mfma_f32_16x16x32_bf16 v[24:27], v[130:133], v[122:125], v[24:27]
	s_cbranch_vccnz .LBB0_786
	ds_read_b64 v[134:135], v116 offset:24576
	ds_read_b64 v[136:137], v117 offset:24576
	ds_read_b64 v[130:131], v116 offset:26624
	ds_read_b64 v[132:133], v117 offset:26624
	v_exp_f32_e32 v96, v96
	v_exp_f32_e32 v97, v97
	v_exp_f32_e32 v98, v98
	v_exp_f32_e32 v99, v99
	v_exp_f32_e32 v88, v88
	v_exp_f32_e32 v89, v89
	v_exp_f32_e32 v90, v90
	v_exp_f32_e32 v91, v91
	v_exp_f32_e32 v84, v84
	v_exp_f32_e32 v85, v85
	v_exp_f32_e32 v86, v86
	v_exp_f32_e32 v87, v87
	v_exp_f32_e32 v80, v80
	v_exp_f32_e32 v81, v81
	v_exp_f32_e32 v82, v82
	v_exp_f32_e32 v83, v83
	v_cvt_pk_bf16_f32 v118, v96, v97
	v_cvt_pk_bf16_f32 v119, v98, v99
	v_cvt_pk_bf16_f32 v120, v84, v85
	v_cvt_pk_bf16_f32 v121, v86, v87
	v_cvt_pk_bf16_f32 v122, v88, v89
	v_cvt_pk_bf16_f32 v123, v90, v91
	v_cvt_pk_bf16_f32 v124, v80, v81
	v_cvt_pk_bf16_f32 v125, v82, v83
	s_waitcnt lgkmcnt(2)
	s_nop 0
	v_mfma_f32_16x16x32_bf16 v[72:75], v[134:137], v[118:121], v[72:75]
	v_mfma_f32_16x16x32_bf16 v[36:39], v[134:137], v[122:125], v[36:39]
	ds_read_b64 v[138:139], v116 offset:28672
	ds_read_b64 v[140:141], v117 offset:28672
	ds_read_b64 v[126:127], v116 offset:30720
	ds_read_b64 v[128:129], v117 offset:30720
	v_exp_f32_e32 v100, v100
	v_exp_f32_e32 v101, v101
	v_mfma_f32_16x16x32_bf16 v[76:79], v[20:23], v[122:125], v[76:79]
	v_exp_f32_e32 v102, v102
	v_exp_f32_e32 v103, v103
	v_exp_f32_e32 v92, v92
	s_waitcnt lgkmcnt(4)
	v_mfma_f32_16x16x32_bf16 v[68:71], v[130:133], v[118:121], v[68:71]
	v_exp_f32_e32 v93, v93
	v_exp_f32_e32 v94, v94
	v_exp_f32_e32 v95, v95
	v_mfma_f32_16x16x32_bf16 v[32:35], v[130:133], v[122:125], v[32:35]
	ds_read_b64 v[134:135], v2 offset:24576
	ds_read_b64 v[136:137], v3 offset:24576
	v_exp_f32_e32 v104, v104
	v_exp_f32_e32 v105, v105
	s_waitcnt lgkmcnt(4)
	v_mfma_f32_16x16x32_bf16 v[28:31], v[138:141], v[122:125], v[28:31]
	v_exp_f32_e32 v106, v106
	v_exp_f32_e32 v107, v107
	v_exp_f32_e32 v108, v108
	s_waitcnt lgkmcnt(2)
	v_mfma_f32_16x16x32_bf16 v[24:27], v[126:129], v[122:125], v[24:27]
	ds_read_b64 v[130:131], v2 offset:26624
	ds_read_b64 v[132:133], v3 offset:26624
	v_exp_f32_e32 v109, v109
	v_exp_f32_e32 v110, v110
	v_mfma_f32_16x16x32_bf16 v[56:59], v[126:129], v[118:121], v[56:59]
	v_exp_f32_e32 v111, v111
	v_mfma_f32_16x16x32_bf16 v[112:115], v[20:23], v[118:121], v[112:115]
	v_cvt_pk_bf16_f32 v116, v100, v101
	v_cvt_pk_bf16_f32 v117, v102, v103
	v_cvt_pk_bf16_f32 v122, v108, v109
	v_mfma_f32_16x16x32_bf16 v[64:67], v[138:141], v[118:121], v[64:67]
	v_cvt_pk_bf16_f32 v118, v104, v105
	v_cvt_pk_bf16_f32 v119, v106, v107
	v_cvt_pk_bf16_f32 v120, v92, v93
	v_cvt_pk_bf16_f32 v121, v94, v95
	v_cvt_pk_bf16_f32 v123, v110, v111
	s_waitcnt lgkmcnt(2)
	s_nop 0
	v_mfma_f32_16x16x32_bf16 v[72:75], v[134:137], v[116:119], v[72:75]
	v_mfma_f32_16x16x32_bf16 v[36:39], v[134:137], v[120:123], v[36:39]
	ds_read_b64 v[126:127], v2 offset:28672
	ds_read_b64 v[128:129], v3 offset:28672
	ds_read_b64 v[138:139], v2 offset:30720
	ds_read_b64 v[140:141], v3 offset:30720
	s_waitcnt lgkmcnt(4)
	v_mfma_f32_16x16x32_bf16 v[68:71], v[130:133], v[116:119], v[68:71]
	v_mfma_f32_16x16x32_bf16 v[32:35], v[130:133], v[120:123], v[32:35]
	v_mfma_f32_16x16x32_bf16 v[112:115], v[20:23], v[116:119], v[112:115]
	v_mfma_f32_16x16x32_bf16 v[76:79], v[20:23], v[120:123], v[76:79]
	s_waitcnt lgkmcnt(2)
	v_mfma_f32_16x16x32_bf16 v[64:67], v[126:129], v[116:119], v[64:67]
	v_mfma_f32_16x16x32_bf16 v[28:31], v[126:129], v[120:123], v[28:31]
	s_waitcnt lgkmcnt(0)
	v_mfma_f32_16x16x32_bf16 v[56:59], v[138:141], v[116:119], v[56:59]
	v_mfma_f32_16x16x32_bf16 v[24:27], v[138:141], v[120:123], v[24:27]
